# P7: second row's XN/MIXB/XSC loads issued together with the first row's (true two rows in flight per wave), on top of v089
# baseline (speedup 1.0000x reference)
.LBB0_807:
	s_ashr_i32 s7, s6, 31
	s_lshl_b64 s[0:1], s[6:7], 6
	s_waitcnt lgkmcnt(0)
	v_lshl_add_u64 v[16:17], v[24:25], 0, s[0:1]
	global_load_dwordx4 v[30:33], v[16:17], off
	s_add_i32 s12, s3, s6
	s_cmp_lt_i32 s12, 0x8000
	s_cselect_b32 s0, s12, s6
	s_ashr_i32 s1, s0, 31
	s_lshl_b64 s[20:21], s[0:1], 6
	s_lshl_b64 s[14:15], s[0:1], 11
	s_lshl_b64 s[0:1], s[0:1], 2
	s_add_u32 s16, s30, s0
	s_addc_u32 s17, s31, s1
	s_lshl_b64 s[0:1], s[6:7], 11
	v_lshl_add_u64 v[28:29], v[22:23], 0, s[0:1]
	global_load_dwordx2 v[34:35], v[28:29], off offset:1536 nt
	v_lshl_add_u64 v[16:17], v[26:27], 0, s[0:1]
	s_lshl_b64 s[0:1], s[6:7], 2
	s_add_u32 s0, s30, s0
	s_addc_u32 s1, s31, s1
	global_load_dwordx2 v[36:37], v[16:17], off offset:512 nt
	global_load_dwordx2 v[38:39], v[28:29], off offset:512 nt
	global_load_dwordx2 v[40:41], v[16:17], off offset:1024 nt
	global_load_dwordx2 v[42:43], v[28:29], off offset:1024 nt
	global_load_dwordx2 v[44:45], v[16:17], off offset:1536 nt
	global_load_dwordx2 v[46:47], v[28:29], off nt
	global_load_dwordx2 v[56:57], v[16:17], off nt
	global_load_dword v58, v21, s[0:1]
	v_lshl_add_u64 v[16:17], v[24:25], 0, s[20:21]
	global_load_dwordx4 v[16:19], v[16:17], off
	v_lshl_add_u64 v[100:101], v[22:23], 0, s[14:15]
	v_lshl_add_u64 v[102:103], v[26:27], 0, s[14:15]
	global_load_dword v90, v21, s[16:17]
	global_load_dwordx2 v[92:93], v[100:101], off nt
	global_load_dwordx2 v[94:95], v[100:101], off offset:512 nt
	global_load_dwordx2 v[96:97], v[100:101], off offset:1024 nt
	global_load_dwordx2 v[98:99], v[100:101], off offset:1536 nt
	global_load_dwordx2 v[104:105], v[102:103], off nt
	global_load_dwordx2 v[106:107], v[102:103], off offset:512 nt
	global_load_dwordx2 v[108:109], v[102:103], off offset:1024 nt
	global_load_dwordx2 v[110:111], v[102:103], off offset:1536 nt
	s_cmpk_gt_i32 s12, 0x7fff
	s_waitcnt vmcnt(19)
	v_mov_b32_e32 v60, v31
	v_mov_b32_e32 v61, v32
	v_mov_b32_e32 v31, v33
	v_pk_add_f32 v[30:31], v[60:61], v[30:31]
	s_waitcnt vmcnt(17)
	v_and_b32_e32 v61, 0xffff0000, v36
	v_add_f32_e32 v30, v30, v31
	ds_bpermute_b32 v32, v20, v30
	v_and_b32_e32 v55, 0xffff0000, v35
	v_lshlrev_b32_e32 v59, 16, v35
	s_waitcnt vmcnt(13)
	v_lshlrev_b32_e32 v70, 16, v44
	v_and_b32_e32 v72, 0xffff0000, v44
	s_waitcnt lgkmcnt(0)
	v_add_f32_e32 v30, v30, v32
	ds_bpermute_b32 v32, v48, v30
	v_lshlrev_b32_e32 v74, 16, v45
	v_and_b32_e32 v76, 0xffff0000, v45
	s_waitcnt vmcnt(11)
	v_lshlrev_b32_e32 v44, 16, v57
	v_and_b32_e32 v45, 0xffff0000, v57
	s_waitcnt lgkmcnt(0)
	v_add_f32_e32 v30, v30, v32
	v_fmamk_f32 v30, v30, 0x3a800000, v53
	v_mul_f32_e32 v32, 0x4f800000, v30
	v_cmp_gt_f32_e32 vcc, s19, v30
	s_waitcnt vmcnt(10)
	v_mul_f32_e32 v57, v58, v55
	v_and_b32_e32 v31, 0xffff0000, v34
	v_cndmask_b32_e32 v30, v30, v32, vcc
	v_sqrt_f32_e32 v32, v30
	v_lshlrev_b32_e32 v33, 16, v34
	v_lshlrev_b32_e32 v35, 16, v36
	v_lshlrev_b32_e32 v34, 16, v38
	v_add_u32_e32 v55, -1, v32
	v_and_b32_e32 v60, 0xffff0000, v38
	v_lshlrev_b32_e32 v62, 16, v39
	v_and_b32_e32 v36, 0xffff0000, v39
	v_lshlrev_b32_e32 v39, 16, v40
	v_lshlrev_b32_e32 v38, 16, v42
	v_and_b32_e32 v65, 0xffff0000, v40
	v_and_b32_e32 v64, 0xffff0000, v42
	v_lshlrev_b32_e32 v66, 16, v43
	v_and_b32_e32 v40, 0xffff0000, v43
	v_lshlrev_b32_e32 v42, 16, v47
	v_and_b32_e32 v43, 0xffff0000, v47
	v_lshlrev_b32_e32 v68, 16, v46
	v_and_b32_e32 v69, 0xffff0000, v46
	v_lshlrev_b32_e32 v46, 16, v56
	v_and_b32_e32 v47, 0xffff0000, v56
	v_mul_f32_e32 v71, v58, v59
	v_add_u32_e32 v56, 1, v32
	v_fma_f32 v59, -v55, v32, v30
	v_fma_f32 v73, -v56, v32, v30
	v_cmp_ge_f32_e64 s[0:1], 0, v59
	v_lshlrev_b32_e32 v63, 16, v37
	v_and_b32_e32 v37, 0xffff0000, v37
	v_cndmask_b32_e64 v32, v32, v55, s[0:1]
	v_cmp_lt_f32_e64 s[0:1], 0, v73
	v_lshlrev_b32_e32 v67, 16, v41
	v_and_b32_e32 v41, 0xffff0000, v41
	v_cndmask_b32_e64 v32, v32, v56, s[0:1]
	v_mul_f32_e32 v55, 0x37800000, v32
	v_cndmask_b32_e32 v32, v32, v55, vcc
	v_cmp_class_f32_e32 vcc, v30, v54
	v_mov_b32_e32 v73, v58
	s_waitcnt vmcnt(9)
	v_add_f32_e32 v16, v16, v17
	v_cndmask_b32_e32 v30, v32, v30, vcc
	v_div_scale_f32 v32, s[0:1], v30, v30, 1.0
	v_rcp_f32_e32 v55, v32
	v_div_scale_f32 v56, vcc, 1.0, v30, 1.0
	v_add_f32_e32 v18, v18, v19
	v_fma_f32 v59, -v32, v55, 1.0
	v_fmac_f32_e32 v55, v59, v55
	v_mul_f32_e32 v59, v56, v55
	v_fma_f32 v75, -v32, v59, v56
	v_fmac_f32_e32 v59, v75, v55
	v_fma_f32 v32, -v32, v59, v56
	v_div_fmas_f32 v32, v32, v55, v59
	v_div_fixup_f32 v59, v32, v30, 1.0
	v_mov_b32_e32 v30, v59
	v_mul_f32_e32 v32, v59, v74
	v_pk_mul_f32 v[44:45], v[30:31], v[44:45] op_sel_hi:[0,1]
	v_pk_mul_f32 v[34:35], v[58:59], v[34:35]
	v_pk_mul_f32 v[60:61], v[58:59], v[60:61]
	v_pk_mul_f32 v[62:63], v[58:59], v[62:63]
	v_pk_mul_f32 v[36:37], v[58:59], v[36:37]
	v_pk_mul_f32 v[38:39], v[58:59], v[38:39]
	v_pk_mul_f32 v[64:65], v[58:59], v[64:65]
	v_pk_mul_f32 v[66:67], v[58:59], v[66:67]
	v_pk_mul_f32 v[40:41], v[58:59], v[40:41]
	v_mul_f32_e32 v75, v59, v70
	v_mul_f32_e32 v77, v59, v72
	v_mul_f32_e32 v55, v59, v76
	v_mul_f32_e32 v59, v2, v32
	v_pk_mul_f32 v[46:47], v[30:31], v[46:47] op_sel_hi:[0,1]
	v_pk_mul_f32 v[44:45], v[14:15], v[44:45]
	v_pk_mul_f32 v[46:47], v[12:13], v[46:47]
	v_pk_fma_f32 v[80:81], v[58:59], v[42:43], v[44:45] op_sel_hi:[0,1,1]
	v_pk_fma_f32 v[68:69], v[58:59], v[68:69], v[46:47] op_sel_hi:[0,1,1]
	v_pk_mov_b32 v[42:43], v[80:81], v[0:1] op_sel:[1,0]
	v_mov_b32_e32 v74, v81
	v_pk_mul_f32 v[42:43], v[42:43], v[74:75]
	v_pk_mov_b32 v[82:83], v[68:69], v[0:1] op_sel:[1,0]
	v_mov_b32_e32 v74, v69
	v_mov_b32_e32 v72, v80
	v_mov_b32_e32 v32, v80
	v_mov_b32_e32 v44, v68
	v_mov_b32_e32 v45, v58
	v_mov_b32_e32 v46, v68
	v_mov_b32_e32 v47, v33
	v_pk_mul_f32 v[74:75], v[82:83], v[74:75]
	v_pk_fma_f32 v[32:33], v[72:73], v[32:33], v[42:43]
	v_pk_fma_f32 v[72:73], v[44:45], v[46:47], v[74:75]
	v_mul_f32_e32 v79, v3, v55
	v_pk_add_f32 v[42:43], v[72:73], v[32:33]
	v_pk_mul_f32 v[32:33], v[72:73], v[32:33]
	v_add_f32_e32 v16, v16, v18
	v_mov_b32_e32 v43, v33
	v_mov_b32_e32 v32, v63
	v_mov_b32_e32 v33, v37
	v_mov_b32_e32 v63, v36
	v_mov_b32_e32 v36, v35
	v_mov_b32_e32 v37, v61
	v_mov_b32_e32 v35, v60
	v_pk_fma_f32 v[60:61], v[8:9], v[36:37], v[34:35]
	v_pk_fma_f32 v[62:63], v[10:11], v[32:33], v[62:63]
	v_mov_b32_e32 v36, v61
	v_mov_b32_e32 v37, v1
	v_mov_b32_e32 v76, v61
	v_mov_b32_e32 v32, v63
	v_mov_b32_e32 v33, v1
	v_mov_b32_e32 v34, v60
	v_mov_b32_e32 v35, v58
	v_mov_b32_e32 v30, v60
	v_pk_mul_f32 v[36:37], v[36:37], v[76:77]
	v_mov_b32_e32 v76, v63
	v_pk_fma_f32 v[74:75], v[34:35], v[30:31], v[36:37]
	v_mov_b32_e32 v34, v62
	v_mov_b32_e32 v30, v62
	v_pk_mul_f32 v[32:33], v[32:33], v[76:77]
	ds_bpermute_b32 v18, v20, v16
	v_pk_fma_f32 v[30:31], v[34:35], v[30:31], v[32:33]
	s_waitcnt lgkmcnt(0)
	v_add_f32_e32 v16, v16, v18
	v_pk_add_f32 v[32:33], v[74:75], v[30:31]
	v_pk_mul_f32 v[30:31], v[74:75], v[30:31]
	v_mov_b32_e32 v74, v73
	v_mov_b32_e32 v33, v31
	v_pk_add_f32 v[30:31], v[42:43], v[32:33]
	v_mov_b32_e32 v32, v67
	v_mov_b32_e32 v33, v41
	v_mov_b32_e32 v67, v40
	v_pk_fma_f32 v[66:67], v[6:7], v[32:33], v[66:67]
	s_nop 0
	v_mov_b32_e32 v78, v66
	v_mov_b32_e32 v56, v66
	v_pk_add_f32 v[56:57], v[78:79], v[56:57]
	v_mul_f32_e32 v32, v67, v67
	v_pk_fma_f32 v[32:33], v[66:67], v[66:67], v[32:33] op_sel_hi:[1,1,0]
	v_pk_mul_f32 v[34:35], v[56:57], v[56:57]
	s_nop 0
	v_mov_b32_e32 v33, v35
	v_mov_b32_e32 v34, v39
	v_mov_b32_e32 v35, v65
	v_mov_b32_e32 v39, v64
	v_pk_fma_f32 v[64:65], v[4:5], v[34:35], v[38:39]
	s_nop 0
	v_mov_b32_e32 v58, v64
	v_mov_b32_e32 v70, v64
	v_pk_add_f32 v[58:59], v[58:59], v[70:71]
	v_mul_f32_e32 v34, v65, v65
	v_pk_fma_f32 v[34:35], v[64:65], v[64:65], v[34:35] op_sel_hi:[1,1,0]
	v_pk_mul_f32 v[36:37], v[58:59], v[58:59]
	v_lshl_add_u64 v[70:71], v[26:27], 0, s[14:15]
	v_mov_b32_e32 v35, v37
	v_pk_add_f32 v[32:33], v[34:35], v[32:33]
	v_lshl_add_u64 v[34:35], v[22:23], 0, s[14:15]
	v_pk_add_f32 v[30:31], v[30:31], v[32:33]
	s_nop 0
	v_add_f32_e32 v31, v30, v31
	ds_bpermute_b32 v32, v20, v31
	s_waitcnt vmcnt(0)
	v_mov_b32_e32 v30, v90
	s_waitcnt lgkmcnt(0)
	v_add_f32_e32 v31, v31, v32
	ds_bpermute_b32 v36, v48, v31
	v_mov_b64_e32 v[32:33], v[92:93]
	v_mov_b64_e32 v[42:43], v[94:95]
	v_mov_b64_e32 v[38:39], v[96:97]
	v_mov_b64_e32 v[46:47], v[98:99]
	s_waitcnt lgkmcnt(0)
	v_add_f32_e32 v31, v31, v36
	v_mov_b64_e32 v[34:35], v[104:105]
	v_mov_b64_e32 v[44:45], v[106:107]
	v_mov_b64_e32 v[40:41], v[108:109]
	v_mov_b64_e32 v[36:37], v[110:111]
	ds_bpermute_b32 v55, v49, v31
	s_waitcnt lgkmcnt(0)
	v_add_f32_e32 v31, v31, v55
	ds_bpermute_b32 v55, v50, v31
	s_waitcnt lgkmcnt(0)
	v_add_f32_e32 v31, v31, v55
	ds_bpermute_b32 v55, v51, v31
	s_waitcnt lgkmcnt(0)
	v_add_f32_e32 v31, v31, v55
	ds_bpermute_b32 v55, v52, v31
	s_waitcnt lgkmcnt(0)
	v_add_f32_e32 v17, v31, v55
	v_fmamk_f32 v17, v17, 0x3a800000, v53
	v_mul_f32_e32 v31, 0x4f800000, v17
	v_cmp_gt_f32_e32 vcc, s19, v17
	s_nop 1
	v_cndmask_b32_e32 v17, v17, v31, vcc
	v_sqrt_f32_e32 v31, v17
	s_nop 0
	v_add_u32_e32 v19, -1, v31
	v_fma_f32 v55, -v19, v31, v17
	v_cmp_ge_f32_e64 s[0:1], 0, v55
	v_add_u32_e32 v55, 1, v31
	s_nop 0
	v_cndmask_b32_e64 v19, v31, v19, s[0:1]
	v_fma_f32 v31, -v55, v31, v17
	v_cmp_lt_f32_e64 s[0:1], 0, v31
	s_nop 1
	v_cndmask_b32_e64 v19, v19, v55, s[0:1]
	v_mul_f32_e32 v31, 0x37800000, v19
	v_cndmask_b32_e32 v19, v19, v31, vcc
	v_cmp_class_f32_e32 vcc, v17, v54
	s_nop 1
	v_cndmask_b32_e32 v19, v19, v17, vcc
	v_div_scale_f32 v31, s[0:1], v19, v19, 1.0
	v_rcp_f32_e32 v55, v31
	ds_bpermute_b32 v17, v48, v16
	v_fma_f32 v18, -v31, v55, 1.0
	v_fmac_f32_e32 v55, v18, v55
	v_div_scale_f32 v18, vcc, 1.0, v19, 1.0
	v_mul_f32_e32 v56, v18, v55
	v_fma_f32 v58, -v31, v56, v18
	v_fmac_f32_e32 v56, v58, v55
	v_fma_f32 v18, -v31, v56, v18
	v_div_fmas_f32 v18, v18, v55, v56
	v_div_fixup_f32 v18, v18, v19, 1.0
	v_pk_mul_f32 v[60:61], v[18:19], v[60:61] op_sel_hi:[0,1]
	v_pk_mul_f32 v[62:63], v[18:19], v[62:63] op_sel_hi:[0,1]
	v_cvt_pk_bf16_f32 v60, v60, v61
	v_cvt_pk_bf16_f32 v61, v62, v63
	global_store_dwordx2 v[28:29], v[60:61], off offset:512
	v_pk_mul_f32 v[60:61], v[18:19], v[64:65] op_sel_hi:[0,1]
	v_pk_mul_f32 v[62:63], v[18:19], v[66:67] op_sel_hi:[0,1]
	v_cvt_pk_bf16_f32 v60, v60, v61
	v_cvt_pk_bf16_f32 v61, v62, v63
	v_mov_b32_e32 v56, v59
	v_pk_mul_f32 v[68:69], v[18:19], v[68:69] op_sel_hi:[0,1]
	v_pk_mul_f32 v[70:71], v[18:19], v[80:81] op_sel_hi:[0,1]
	global_store_dwordx2 v[28:29], v[60:61], off offset:1024
	v_pk_mul_f32 v[60:61], v[18:19], v[74:75] op_sel_hi:[0,1]
	v_pk_mul_f32 v[18:19], v[18:19], v[56:57] op_sel_hi:[0,1]
	v_cvt_pk_bf16_f32 v68, v68, v69
	v_cvt_pk_bf16_f32 v69, v70, v71
	v_cvt_pk_bf16_f32 v58, v60, v61
	v_cvt_pk_bf16_f32 v59, v18, v19
	global_store_dwordx2 v[28:29], v[68:69], off
	global_store_dwordx2 v[28:29], v[58:59], off offset:1536
	s_cbranch_scc1 .LBB0_806
	s_waitcnt lgkmcnt(0)
	v_add_f32_e32 v16, v16, v17
	v_fmamk_f32 v16, v16, 0x3a800000, v53
	v_mul_f32_e32 v17, 0x4f800000, v16
	v_cmp_gt_f32_e32 vcc, s19, v16
	s_waitcnt vmcnt(8)
	v_lshlrev_b32_e32 v19, 16, v47
	s_waitcnt vmcnt(6)
	v_lshlrev_b32_e32 v57, 16, v44
	v_cndmask_b32_e32 v16, v16, v17, vcc
	v_sqrt_f32_e32 v18, v16
	v_and_b32_e32 v17, 0xffff0000, v47
	v_lshlrev_b32_e32 v47, 16, v46
	v_and_b32_e32 v59, 0xffff0000, v44
	v_add_u32_e32 v28, -1, v18
	v_fma_f32 v29, -v28, v18, v16
	v_cmp_ge_f32_e64 s[0:1], 0, v29
	v_add_u32_e32 v29, 1, v18
	v_lshlrev_b32_e32 v61, 16, v45
	v_cndmask_b32_e64 v28, v18, v28, s[0:1]
	v_fma_f32 v18, -v29, v18, v16
	v_cmp_lt_f32_e64 s[0:1], 0, v18
	v_and_b32_e32 v45, 0xffff0000, v45
	v_and_b32_e32 v44, 0xffff0000, v43
	v_cndmask_b32_e64 v18, v28, v29, s[0:1]
	v_mul_f32_e32 v28, 0x37800000, v18
	v_cndmask_b32_e32 v18, v18, v28, vcc
	v_cmp_class_f32_e32 vcc, v16, v54
	v_and_b32_e32 v29, 0xffff0000, v46
	v_lshlrev_b32_e32 v56, 16, v42
	v_cndmask_b32_e32 v16, v18, v16, vcc
	v_div_scale_f32 v18, s[0:1], v16, v16, 1.0
	v_rcp_f32_e32 v28, v18
	v_and_b32_e32 v58, 0xffff0000, v42
	v_lshlrev_b32_e32 v60, 16, v43
	s_waitcnt vmcnt(5)
	v_and_b32_e32 v63, 0xffff0000, v40
	v_fma_f32 v31, -v18, v28, 1.0
	v_fmac_f32_e32 v28, v31, v28
	v_div_scale_f32 v31, vcc, 1.0, v16, 1.0
	v_mul_f32_e32 v46, v31, v28
	v_fma_f32 v55, -v18, v46, v31
	v_fmac_f32_e32 v46, v55, v28
	v_fma_f32 v18, -v18, v46, v31
	v_div_fmas_f32 v18, v18, v28, v46
	v_div_fixup_f32 v31, v18, v16, 1.0
	v_pk_mul_f32 v[42:43], v[30:31], v[44:45]
	v_lshlrev_b32_e32 v45, 16, v40
	v_lshlrev_b32_e32 v65, 16, v41
	v_and_b32_e32 v41, 0xffff0000, v41
	v_and_b32_e32 v40, 0xffff0000, v39
	s_waitcnt vmcnt(4)
	v_lshlrev_b32_e32 v16, 16, v36
	v_lshlrev_b32_e32 v44, 16, v38
	v_and_b32_e32 v62, 0xffff0000, v38
	v_lshlrev_b32_e32 v64, 16, v39
	v_pk_mul_f32 v[38:39], v[30:31], v[40:41]
	v_mul_f32_e32 v41, v31, v16
	v_and_b32_e32 v16, 0xffff0000, v36
	v_mul_f32_e32 v67, v31, v16
	v_lshlrev_b32_e32 v16, 16, v37
	v_mul_f32_e32 v16, v31, v16
	v_mul_f32_e32 v69, v2, v16
	v_and_b32_e32 v16, 0xffff0000, v37
	v_mul_f32_e32 v16, v31, v16
	v_mul_f32_e32 v17, v30, v17
	v_mul_f32_e32 v37, v3, v16
	v_lshlrev_b32_e32 v72, 16, v35
	v_and_b32_e32 v73, 0xffff0000, v35
	v_mov_b32_e32 v16, v31
	v_pk_mul_f32 v[72:73], v[16:17], v[72:73] op_sel_hi:[0,1]
	v_lshlrev_b32_e32 v70, 16, v33
	v_and_b32_e32 v71, 0xffff0000, v33
	v_pk_mul_f32 v[72:73], v[14:15], v[72:73]
	v_and_b32_e32 v33, 0xffff0000, v34
	v_pk_fma_f32 v[70:71], v[30:31], v[70:71], v[72:73] op_sel_hi:[0,1,1]
	v_lshlrev_b32_e32 v72, 16, v32
	v_and_b32_e32 v73, 0xffff0000, v32
	v_lshlrev_b32_e32 v32, 16, v34
	v_pk_mul_f32 v[32:33], v[16:17], v[32:33] op_sel_hi:[0,1]
	v_pk_mul_f32 v[32:33], v[12:13], v[32:33]
	v_mov_b32_e32 v40, v71
	v_pk_fma_f32 v[32:33], v[30:31], v[72:73], v[32:33] op_sel_hi:[0,1,1]
	v_pk_mov_b32 v[72:73], v[70:71], v[0:1] op_sel:[1,0]
	v_pk_mov_b32 v[78:79], v[32:33], v[0:1] op_sel:[1,0]
	v_pk_mul_f32 v[72:73], v[72:73], v[40:41]
	v_mov_b32_e32 v40, v33
	v_mov_b32_e32 v34, v70
	v_mov_b32_e32 v35, v30
	v_mov_b32_e32 v46, v70
	v_mov_b32_e32 v74, v32
	v_mov_b32_e32 v75, v30
	v_mov_b32_e32 v76, v32
	v_mov_b32_e32 v77, v47
	v_pk_mul_f32 v[40:41], v[78:79], v[40:41]
	v_pk_fma_f32 v[34:35], v[34:35], v[46:47], v[72:73]
	v_pk_fma_f32 v[40:41], v[74:75], v[76:77], v[40:41]
	v_pk_mul_f32 v[60:61], v[30:31], v[60:61]
	v_pk_add_f32 v[46:47], v[40:41], v[34:35]
	v_pk_mul_f32 v[34:35], v[40:41], v[34:35]
	v_pk_mul_f32 v[56:57], v[30:31], v[56:57]
	v_pk_mul_f32 v[58:59], v[30:31], v[58:59]
	v_mov_b32_e32 v47, v35
	v_mov_b32_e32 v34, v61
	v_mov_b32_e32 v35, v43
	v_mov_b32_e32 v61, v42
	v_pk_fma_f32 v[34:35], v[10:11], v[34:35], v[60:61]
	v_mov_b32_e32 v60, v57
	v_mov_b32_e32 v61, v59
	v_mov_b32_e32 v57, v58
	v_pk_fma_f32 v[56:57], v[8:9], v[60:61], v[56:57]
	v_mov_b32_e32 v61, v1
	v_mov_b32_e32 v60, v57
	v_mov_b32_e32 v66, v57
	v_mov_b32_e32 v42, v35
	v_mov_b32_e32 v43, v1
	v_mov_b32_e32 v58, v56
	v_mov_b32_e32 v59, v30
	v_mov_b32_e32 v28, v56
	v_pk_mul_f32 v[60:61], v[60:61], v[66:67]
	v_mov_b32_e32 v66, v35
	v_mul_f32_e32 v19, v30, v19
	v_pk_mul_f32 v[44:45], v[30:31], v[44:45]
	v_pk_mul_f32 v[62:63], v[30:31], v[62:63]
	v_pk_mul_f32 v[64:65], v[30:31], v[64:65]
	v_pk_fma_f32 v[58:59], v[58:59], v[28:29], v[60:61]
	v_mov_b32_e32 v60, v34
	v_mov_b32_e32 v61, v30
	v_mov_b32_e32 v28, v34
	v_pk_mul_f32 v[30:31], v[42:43], v[66:67]
	s_ashr_i32 s13, s12, 31
	v_pk_fma_f32 v[28:29], v[60:61], v[28:29], v[30:31]
	s_nop 0
	v_pk_add_f32 v[30:31], v[58:59], v[28:29]
	v_pk_mul_f32 v[28:29], v[58:59], v[28:29]
	v_mov_b32_e32 v58, v41
	v_mov_b32_e32 v31, v29
	v_pk_add_f32 v[28:29], v[46:47], v[30:31]
	v_mov_b32_e32 v30, v65
	v_mov_b32_e32 v31, v39
	v_mov_b32_e32 v65, v38
	v_pk_fma_f32 v[30:31], v[6:7], v[30:31], v[64:65]
	s_nop 0
	v_mov_b32_e32 v36, v30
	v_mov_b32_e32 v16, v30
	v_pk_add_f32 v[16:17], v[36:37], v[16:17]
	v_mul_f32_e32 v18, v31, v31
	v_pk_fma_f32 v[36:37], v[30:31], v[30:31], v[18:19] op_sel_hi:[1,1,0]
	v_pk_mul_f32 v[38:39], v[16:17], v[16:17]
	s_nop 0
	v_mov_b32_e32 v37, v39
	v_mov_b32_e32 v38, v45
	v_mov_b32_e32 v39, v63
	v_mov_b32_e32 v45, v62
	v_pk_fma_f32 v[38:39], v[4:5], v[38:39], v[44:45]
	s_nop 0
	v_mov_b32_e32 v68, v38
	v_mov_b32_e32 v18, v38
	v_pk_add_f32 v[18:19], v[68:69], v[18:19]
	v_mul_f32_e32 v16, v39, v39
	v_pk_fma_f32 v[42:43], v[38:39], v[38:39], v[16:17] op_sel_hi:[1,1,0]
	v_pk_mul_f32 v[44:45], v[18:19], v[18:19]
	s_nop 0
	v_mov_b32_e32 v43, v45
	v_pk_add_f32 v[36:37], v[42:43], v[36:37]
	s_nop 0
	v_pk_add_f32 v[28:29], v[28:29], v[36:37]
	s_nop 0
	v_add_f32_e32 v16, v28, v29
	ds_bpermute_b32 v18, v20, v16
	s_waitcnt lgkmcnt(0)
	v_add_f32_e32 v16, v16, v18
	ds_bpermute_b32 v18, v48, v16
	s_waitcnt lgkmcnt(0)
	v_add_f32_e32 v16, v16, v18
	ds_bpermute_b32 v18, v49, v16
	s_waitcnt lgkmcnt(0)
	v_add_f32_e32 v16, v16, v18
	ds_bpermute_b32 v18, v50, v16
	s_waitcnt lgkmcnt(0)
	v_add_f32_e32 v16, v16, v18
	ds_bpermute_b32 v18, v51, v16
	s_waitcnt lgkmcnt(0)
	v_add_f32_e32 v16, v16, v18
	ds_bpermute_b32 v18, v52, v16
	s_waitcnt lgkmcnt(0)
	v_add_f32_e32 v16, v16, v18
	v_fmamk_f32 v16, v16, 0x3a800000, v53
	v_mul_f32_e32 v18, 0x4f800000, v16
	v_cmp_gt_f32_e32 vcc, s19, v16
	s_nop 1
	v_cndmask_b32_e32 v16, v16, v18, vcc
	v_sqrt_f32_e32 v18, v16
	s_nop 0
	v_add_u32_e32 v28, -1, v18
	v_fma_f32 v29, -v28, v18, v16
	v_cmp_ge_f32_e64 s[0:1], 0, v29
	v_add_u32_e32 v29, 1, v18
	s_nop 0
	v_cndmask_b32_e64 v28, v18, v28, s[0:1]
	v_fma_f32 v18, -v29, v18, v16
	v_cmp_lt_f32_e64 s[0:1], 0, v18
	s_nop 1
	v_cndmask_b32_e64 v18, v28, v29, s[0:1]
	v_mul_f32_e32 v28, 0x37800000, v18
	v_cndmask_b32_e32 v18, v18, v28, vcc
	v_cmp_class_f32_e32 vcc, v16, v54
	s_nop 1
	v_cndmask_b32_e32 v16, v18, v16, vcc
	v_div_scale_f32 v18, s[0:1], v16, v16, 1.0
	v_rcp_f32_e32 v36, v18
	s_lshl_b64 s[0:1], s[12:13], 11
	v_lshl_add_u64 v[28:29], v[22:23], 0, s[0:1]
	v_fma_f32 v37, -v18, v36, 1.0
	v_fmac_f32_e32 v36, v37, v36
	v_div_scale_f32 v37, vcc, 1.0, v16, 1.0
	v_mul_f32_e32 v40, v37, v36
	v_fma_f32 v42, -v18, v40, v37
	v_fmac_f32_e32 v40, v42, v36
	v_fma_f32 v18, -v18, v40, v37
	v_div_fmas_f32 v18, v18, v36, v40
	v_div_fixup_f32 v18, v18, v16, 1.0
	v_pk_mul_f32 v[32:33], v[18:19], v[32:33] op_sel_hi:[0,1]
	v_pk_mul_f32 v[36:37], v[18:19], v[70:71] op_sel_hi:[0,1]
	v_cvt_pk_bf16_f32 v32, v32, v33
	v_cvt_pk_bf16_f32 v33, v36, v37
	global_store_dwordx2 v[28:29], v[32:33], off
	v_pk_mul_f32 v[32:33], v[18:19], v[56:57] op_sel_hi:[0,1]
	v_pk_mul_f32 v[34:35], v[18:19], v[34:35] op_sel_hi:[0,1]
	v_cvt_pk_bf16_f32 v32, v32, v33
	v_cvt_pk_bf16_f32 v33, v34, v35
	global_store_dwordx2 v[28:29], v[32:33], off offset:512
	v_pk_mul_f32 v[32:33], v[18:19], v[38:39] op_sel_hi:[0,1]
	v_pk_mul_f32 v[30:31], v[18:19], v[30:31] op_sel_hi:[0,1]
	v_mov_b32_e32 v16, v19
	v_cvt_pk_bf16_f32 v32, v32, v33
	v_cvt_pk_bf16_f32 v33, v30, v31
	v_pk_mul_f32 v[30:31], v[18:19], v[58:59] op_sel_hi:[0,1]
	v_pk_mul_f32 v[16:17], v[18:19], v[16:17] op_sel_hi:[0,1]
	v_cvt_pk_bf16_f32 v30, v30, v31
	v_cvt_pk_bf16_f32 v31, v16, v17
	global_store_dwordx2 v[28:29], v[32:33], off offset:1024
	global_store_dwordx2 v[28:29], v[30:31], off offset:1536
	s_branch .LBB0_806
